# nt also on the sample K/V bf16 image stores in cache_tail (each read once by a sample attention item)
# baseline (speedup 1.0000x reference)
.LBB0_421:
	s_or_b64 exec, exec, s[26:27]
	v_lshlrev_b32_e32 v2, 8, v46
	v_lshlrev_b32_e32 v3, 3, v46
	s_mov_b64 s[26:27], -1
	s_cmpk_gt_i32 s38, 0x1fff
	v_and_b32_e32 v38, 0xe00, v2
	v_and_b32_e32 v34, 8, v3
	v_and_b32_e32 v40, 0x800, v2
	v_and_b32_e32 v36, 56, v3
	s_cbranch_scc0 .LBB0_431
	s_load_dwordx4 s[28:31], s[20:21], 0x10
	s_add_i32 s26, s38, 0xffffe000
	v_lshlrev_b32_e32 v2, 2, v46
	v_lshl_add_u32 v2, s26, 10, v2
	v_ashrrev_i32_e32 v3, 31, v2
	v_lshlrev_b64 v[2:3], 2, v[2:3]
	s_waitcnt lgkmcnt(0)
	v_lshl_add_u64 v[42:43], s[28:29], 0, v[2:3]
	v_lshl_add_u64 v[44:45], s[30:31], 0, v[2:3]
	global_load_dwordx4 v[26:29], v[42:43], off nt
	global_load_dwordx4 v[22:25], v[42:43], off offset:1024 nt
	global_load_dwordx4 v[30:33], v[44:45], off nt
	global_load_dwordx4 v[18:21], v[44:45], off offset:1024 nt
	global_load_dwordx4 v[10:13], v[42:43], off offset:2048 nt
	global_load_dwordx4 v[6:9], v[42:43], off offset:3072 nt
	global_load_dwordx4 v[14:17], v[44:45], off offset:2048 nt
	global_load_dwordx4 v[2:5], v[44:45], off offset:3072 nt
	v_mov_b32_e32 v41, v35
	v_lshl_add_u32 v47, s26, 8, v46
	v_mov_b32_e32 v39, v35
	v_lshl_add_u64 v[42:43], s[8:9], 0, v[40:41]
	v_lshlrev_b32_e32 v41, 2, v47
	v_lshl_add_u64 v[44:45], s[6:7], 0, v[38:39]
	v_ashrrev_i32_e32 v39, 12, v47
	v_lshrrev_b32_e32 v49, 5, v47
	v_bfe_u32 v54, v41, 6, 1
	v_bfe_u32 v49, v49, 5, 2
	v_lshl_or_b32 v54, v39, 1, v54
	v_mad_i32_i24 v54, v54, 5, v49
	v_ashrrev_i32_e32 v55, 31, v54
	v_bfe_u32 v52, v47, 5, 5
	v_lshlrev_b64 v[54:55], 12, v[54:55]
	v_mov_b32_e32 v51, v35
	v_mov_b32_e32 v53, v35
	v_lshlrev_b32_e32 v50, 4, v52
	v_lshlrev_b32_e32 v52, 6, v52
	v_lshl_add_u64 v[56:57], v[44:45], 0, v[54:55]
	v_lshl_add_u64 v[54:55], v[42:43], 0, v[54:55]
	v_lshl_add_u64 v[50:51], v[56:57], 0, v[50:51]
	v_lshl_add_u64 v[52:53], v[54:55], 0, v[52:53]
	v_bfe_u32 v48, v47, 5, 7
	v_mov_b32_e32 v37, v35
	v_lshl_add_u64 v[50:51], v[50:51], 0, v[34:35]
	v_cmp_lt_u32_e32 vcc, 31, v48
	v_lshl_add_u64 v[52:53], v[52:53], 0, v[36:37]
	s_waitcnt vmcnt(0)
	v_mov_b32_e32 v54, v26
	v_mov_b32_e32 v55, v22
	v_mov_b32_e32 v56, v30
	v_mov_b32_e32 v57, v18
	v_mov_b32_e32 v58, v10
	v_mov_b32_e32 v59, v6
	v_mov_b32_e32 v60, v14
	v_mov_b32_e32 v61, v2
	v_bfe_u32 v49, v26, 16, 1
	v_bfe_u32 v63, v28, 16, 1
	v_pk_add_f32 v[54:55], v[54:55], v[56:57]
	v_bfe_u32 v62, v27, 16, 1
	v_bfe_u32 v64, v29, 16, 1
	v_bfe_u32 v65, v30, 16, 1
	v_bfe_u32 v67, v32, 16, 1
	v_pk_add_f32 v[56:57], v[58:59], v[60:61]
	v_add3_u32 v49, v26, v49, s36
	v_add3_u32 v59, v28, v63, s36
	v_add_f32_e32 v54, 0, v54
	v_bfe_u32 v66, v31, 16, 1
	v_bfe_u32 v68, v33, 16, 1
	v_add3_u32 v58, v27, v62, s36
	v_add3_u32 v60, v29, v64, s36
	v_add3_u32 v61, v30, v65, s36
	v_add3_u32 v63, v32, v67, s36
	v_lshrrev_b32_e32 v49, 16, v49
	v_lshrrev_b32_e32 v59, 16, v59
	v_add_f32_e32 v65, v54, v55
	v_add3_u32 v62, v31, v66, s36
	v_add3_u32 v64, v33, v68, s36
	v_lshrrev_b32_e32 v61, 16, v61
	v_lshrrev_b32_e32 v63, 16, v63
	v_and_or_b32 v54, v58, s37, v49
	v_and_or_b32 v55, v60, s37, v59
	v_add_f32_e32 v49, v65, v56
	v_and_or_b32 v58, v62, s37, v61
	v_and_or_b32 v59, v64, s37, v63
	v_add_f32_e32 v49, v49, v57
	global_store_dwordx2 v[50:51], v[54:55], off sc1 nt
	global_store_dwordx2 v[52:53], v[58:59], off sc1 nt
	s_and_saveexec_b64 s[26:27], vcc
	s_cbranch_execz .LBB0_424
	v_lshl_or_b32 v39, v39, 7, v48
	v_subrev_u32_e32 v48, 32, v39
	v_ashrrev_i32_e32 v49, 31, v48
	v_and_b32_e32 v41, 0x7c, v41
	v_lshlrev_b64 v[48:49], 9, v[48:49]
	v_lshl_or_b32 v48, v41, 2, v48
	v_lshl_add_u64 v[50:51], s[10:11], 0, v[48:49]
	global_store_dwordx4 v[50:51], v[26:29], off sc0 sc1 nt
	s_nop 1
	v_lshl_add_u64 v[26:27], s[12:13], 0, v[48:49]
	global_store_dwordx4 v[26:27], v[30:33], off sc0 sc1 nt
	s_nop 1
.LBB0_424:
	s_or_b64 exec, exec, s[26:27]
	v_add_u32_e32 v29, 64, v47
	v_lshlrev_b32_e32 v27, 2, v29
	v_ashrrev_i32_e32 v26, 12, v29
	v_lshrrev_b32_e32 v30, 5, v29
	v_bfe_u32 v31, v27, 6, 1
	v_lshl_or_b32 v31, v26, 1, v31
	v_bfe_u32 v30, v30, 5, 2
	v_mad_i32_i24 v30, v31, 5, v30
	v_ashrrev_i32_e32 v31, 31, v30
	v_bfe_u32 v39, v22, 16, 1
	v_bfe_u32 v28, v29, 5, 7
	v_lshlrev_b64 v[30:31], 12, v[30:31]
	v_bfe_u32 v29, v29, 5, 5
	v_add3_u32 v39, v22, v39, s36
	v_bfe_u32 v41, v23, 16, 1
	v_lshl_add_u64 v[32:33], v[44:45], 0, v[30:31]
	v_lshlrev_b32_e32 v48, 4, v29
	v_mov_b32_e32 v49, v35
	v_lshrrev_b32_e32 v39, 16, v39
	v_add3_u32 v41, v23, v41, s36
	v_lshl_add_u64 v[32:33], v[32:33], 0, v[48:49]
	v_and_or_b32 v48, v41, s37, v39
	v_bfe_u32 v39, v24, 16, 1
	v_add3_u32 v39, v24, v39, s36
	v_bfe_u32 v41, v25, 16, 1
	v_lshrrev_b32_e32 v39, 16, v39
	v_add3_u32 v41, v25, v41, s36
	v_lshl_add_u64 v[32:33], v[32:33], 0, v[34:35]
	v_and_or_b32 v49, v41, s37, v39
	global_store_dwordx2 v[32:33], v[48:49], off sc1 nt
	v_lshl_add_u64 v[30:31], v[42:43], 0, v[30:31]
	v_lshlrev_b32_e32 v32, 6, v29
	v_mov_b32_e32 v33, v35
	v_bfe_u32 v29, v18, 16, 1
	v_lshl_add_u64 v[30:31], v[30:31], 0, v[32:33]
	v_add3_u32 v29, v18, v29, s36
	v_bfe_u32 v32, v19, 16, 1
	v_lshrrev_b32_e32 v29, 16, v29
	v_add3_u32 v32, v19, v32, s36
	v_and_or_b32 v32, v32, s37, v29
	v_bfe_u32 v29, v20, 16, 1
	v_add3_u32 v29, v20, v29, s36
	v_bfe_u32 v33, v21, 16, 1
	v_lshrrev_b32_e32 v29, 16, v29
	v_add3_u32 v33, v21, v33, s36
	v_lshl_add_u64 v[30:31], v[30:31], 0, v[36:37]
	v_and_or_b32 v33, v33, s37, v29
	v_cmp_lt_u32_e32 vcc, 31, v28
	global_store_dwordx2 v[30:31], v[32:33], off sc1 nt
	s_and_saveexec_b64 s[26:27], vcc
	s_cbranch_execz .LBB0_426
	v_lshl_or_b32 v26, v26, 7, v28
	v_subrev_u32_e32 v26, 32, v26
	v_and_b32_e32 v29, 0x7c, v27
	v_ashrrev_i32_e32 v27, 31, v26
	v_lshlrev_b64 v[26:27], 9, v[26:27]
	v_lshl_or_b32 v26, v29, 2, v26
	v_lshl_add_u64 v[28:29], s[10:11], 0, v[26:27]
	global_store_dwordx4 v[28:29], v[22:25], off sc0 sc1 nt
	s_nop 1
	v_lshl_add_u64 v[22:23], s[12:13], 0, v[26:27]
	global_store_dwordx4 v[22:23], v[18:21], off sc0 sc1 nt
	s_nop 1
.LBB0_426:
	s_or_b64 exec, exec, s[26:27]
	v_add_u32_e32 v21, 0x80, v47
	v_lshlrev_b32_e32 v19, 2, v21
	v_ashrrev_i32_e32 v18, 12, v21
	v_lshrrev_b32_e32 v22, 5, v21
	v_bfe_u32 v23, v19, 6, 1
	v_lshl_or_b32 v23, v18, 1, v23
	v_bfe_u32 v22, v22, 5, 2
	v_mad_i32_i24 v22, v23, 5, v22
	v_ashrrev_i32_e32 v23, 31, v22
	v_bfe_u32 v20, v21, 5, 7
	v_lshlrev_b64 v[22:23], 12, v[22:23]
	v_bfe_u32 v21, v21, 5, 5
	v_lshl_add_u64 v[24:25], v[44:45], 0, v[22:23]
	v_lshlrev_b32_e32 v26, 4, v21
	v_mov_b32_e32 v27, v35
	v_lshl_add_u64 v[24:25], v[24:25], 0, v[26:27]
	v_bfe_u32 v26, v10, 16, 1
	v_add3_u32 v26, v10, v26, s36
	v_bfe_u32 v27, v11, 16, 1
	v_lshrrev_b32_e32 v26, 16, v26
	v_add3_u32 v27, v11, v27, s36
	v_and_or_b32 v26, v27, s37, v26
	v_bfe_u32 v27, v12, 16, 1
	v_add3_u32 v27, v12, v27, s36
	v_bfe_u32 v28, v13, 16, 1
	v_lshrrev_b32_e32 v27, 16, v27
	v_add3_u32 v28, v13, v28, s36
	v_lshl_add_u64 v[24:25], v[24:25], 0, v[34:35]
	v_and_or_b32 v27, v28, s37, v27
	global_store_dwordx2 v[24:25], v[26:27], off sc1 nt
	v_lshl_add_u64 v[22:23], v[42:43], 0, v[22:23]
	v_lshlrev_b32_e32 v24, 6, v21
	v_mov_b32_e32 v25, v35
	v_bfe_u32 v21, v14, 16, 1
	v_lshl_add_u64 v[22:23], v[22:23], 0, v[24:25]
	v_add3_u32 v21, v14, v21, s36
	v_bfe_u32 v24, v15, 16, 1
	v_lshrrev_b32_e32 v21, 16, v21
	v_add3_u32 v24, v15, v24, s36
	v_and_or_b32 v24, v24, s37, v21
	v_bfe_u32 v21, v16, 16, 1
	v_add3_u32 v21, v16, v21, s36
	v_bfe_u32 v25, v17, 16, 1
	v_lshrrev_b32_e32 v21, 16, v21
	v_add3_u32 v25, v17, v25, s36
	v_lshl_add_u64 v[22:23], v[22:23], 0, v[36:37]
	v_and_or_b32 v25, v25, s37, v21
	v_cmp_lt_u32_e32 vcc, 31, v20
	global_store_dwordx2 v[22:23], v[24:25], off sc1 nt
	s_and_saveexec_b64 s[26:27], vcc
	s_cbranch_execz .LBB0_428
	v_lshl_or_b32 v18, v18, 7, v20
	v_subrev_u32_e32 v18, 32, v18
	v_and_b32_e32 v21, 0x7c, v19
	v_ashrrev_i32_e32 v19, 31, v18
	v_lshlrev_b64 v[18:19], 9, v[18:19]
	v_lshl_or_b32 v18, v21, 2, v18
	v_lshl_add_u64 v[20:21], s[10:11], 0, v[18:19]
	global_store_dwordx4 v[20:21], v[10:13], off sc0 sc1 nt
	s_nop 1
	v_lshl_add_u64 v[10:11], s[12:13], 0, v[18:19]
	global_store_dwordx4 v[10:11], v[14:17], off sc0 sc1 nt
	s_nop 1
.LBB0_428:
	s_or_b64 exec, exec, s[26:27]
	v_add_u32_e32 v13, 0xc0, v47
	v_lshlrev_b32_e32 v11, 2, v13
	v_ashrrev_i32_e32 v10, 12, v13
	v_lshrrev_b32_e32 v14, 5, v13
	v_bfe_u32 v15, v11, 6, 1
	v_lshl_or_b32 v15, v10, 1, v15
	v_bfe_u32 v14, v14, 5, 2
	v_mad_i32_i24 v14, v15, 5, v14
	v_ashrrev_i32_e32 v15, 31, v14
	v_bfe_u32 v12, v13, 5, 7
	v_lshlrev_b64 v[14:15], 12, v[14:15]
	v_bfe_u32 v13, v13, 5, 5
	v_lshl_add_u64 v[16:17], v[44:45], 0, v[14:15]
	v_lshlrev_b32_e32 v18, 4, v13
	v_mov_b32_e32 v19, v35
	v_lshl_add_u64 v[16:17], v[16:17], 0, v[18:19]
	v_bfe_u32 v18, v6, 16, 1
	v_add3_u32 v18, v6, v18, s36
	v_bfe_u32 v19, v7, 16, 1
	v_lshrrev_b32_e32 v18, 16, v18
	v_add3_u32 v19, v7, v19, s36
	v_and_or_b32 v18, v19, s37, v18
	v_bfe_u32 v19, v8, 16, 1
	v_add3_u32 v19, v8, v19, s36
	v_bfe_u32 v20, v9, 16, 1
	v_lshrrev_b32_e32 v19, 16, v19
	v_add3_u32 v20, v9, v20, s36
	v_lshl_add_u64 v[16:17], v[16:17], 0, v[34:35]
	v_and_or_b32 v19, v20, s37, v19
	global_store_dwordx2 v[16:17], v[18:19], off sc1 nt
	v_lshl_add_u64 v[14:15], v[42:43], 0, v[14:15]
	v_lshlrev_b32_e32 v16, 6, v13
	v_mov_b32_e32 v17, v35
	v_bfe_u32 v13, v2, 16, 1
	v_lshl_add_u64 v[14:15], v[14:15], 0, v[16:17]
	v_add3_u32 v13, v2, v13, s36
	v_bfe_u32 v16, v3, 16, 1
	v_lshrrev_b32_e32 v13, 16, v13
	v_add3_u32 v16, v3, v16, s36
	v_and_or_b32 v16, v16, s37, v13
	v_bfe_u32 v13, v4, 16, 1
	v_add3_u32 v13, v4, v13, s36
	v_bfe_u32 v17, v5, 16, 1
	v_lshrrev_b32_e32 v13, 16, v13
	v_add3_u32 v17, v5, v17, s36
	v_lshl_add_u64 v[14:15], v[14:15], 0, v[36:37]
	v_and_or_b32 v17, v17, s37, v13
	v_cmp_lt_u32_e32 vcc, 31, v12
	global_store_dwordx2 v[14:15], v[16:17], off sc1 nt
	s_and_saveexec_b64 s[26:27], vcc
	s_cbranch_execz .LBB0_430
	v_lshl_or_b32 v10, v10, 7, v12
	v_subrev_u32_e32 v10, 32, v10
	v_and_b32_e32 v13, 0x7c, v11
	v_ashrrev_i32_e32 v11, 31, v10
	v_lshlrev_b64 v[10:11], 9, v[10:11]
	v_lshl_or_b32 v10, v13, 2, v10
	v_lshl_add_u64 v[12:13], s[10:11], 0, v[10:11]
	global_store_dwordx4 v[12:13], v[6:9], off sc0 sc1 nt
	s_nop 1
	v_lshl_add_u64 v[6:7], s[12:13], 0, v[10:11]
	global_store_dwordx4 v[6:7], v[2:5], off sc0 sc1 nt
	s_nop 1

.LBB0_431:
	s_and_b64 vcc, exec, s[26:27]
	s_cbranch_vccz .LBB0_416
	s_load_dwordx4 s[28:31], s[20:21], 0x20
	s_lshl_b32 s26, s38, 10
	v_lshl_add_u32 v2, v46, 2, s26
	v_ashrrev_i32_e32 v3, 31, v2
	v_lshlrev_b64 v[2:3], 2, v[2:3]
	s_waitcnt lgkmcnt(0)
	v_lshl_add_u64 v[42:43], s[28:29], 0, v[2:3]
	v_lshl_add_u64 v[44:45], s[30:31], 0, v[2:3]
	global_load_dwordx4 v[26:29], v[42:43], off nt
	global_load_dwordx4 v[22:25], v[42:43], off offset:1024 nt
	global_load_dwordx4 v[30:33], v[44:45], off nt
	global_load_dwordx4 v[18:21], v[44:45], off offset:1024 nt
	global_load_dwordx4 v[10:13], v[42:43], off offset:2048 nt
	global_load_dwordx4 v[6:9], v[42:43], off offset:3072 nt
	global_load_dwordx4 v[14:17], v[44:45], off offset:2048 nt
	global_load_dwordx4 v[2:5], v[44:45], off offset:3072 nt
	v_lshl_add_u32 v44, s38, 8, v46
	v_mov_b32_e32 v39, v35
	v_mov_b32_e32 v41, v35
	v_lshl_add_u64 v[42:43], s[14:15], 0, v[38:39]
	v_lshl_add_u64 v[38:39], s[18:19], 0, v[40:41]
	v_lshlrev_b32_e32 v41, 2, v44
	v_ashrrev_i32_e32 v40, 16, v44
	v_lshrrev_b32_e32 v46, 7, v44
	v_bfe_u32 v50, v41, 6, 3
	v_bfe_u32 v51, v46, 5, 4
	v_lshl_or_b32 v50, v40, 3, v50
	v_mad_i32_i24 v50, v50, 17, v51
	v_ashrrev_i32_e32 v51, 31, v50
	v_bfe_u32 v48, v44, 7, 5
	v_lshlrev_b64 v[50:51], 12, v[50:51]
	v_mov_b32_e32 v47, v35
	v_mov_b32_e32 v49, v35
	v_lshlrev_b32_e32 v46, 4, v48
	v_lshlrev_b32_e32 v48, 6, v48
	v_lshl_add_u64 v[52:53], v[42:43], 0, v[50:51]
	v_lshl_add_u64 v[50:51], v[38:39], 0, v[50:51]
	v_lshl_add_u64 v[46:47], v[52:53], 0, v[46:47]
	v_lshl_add_u64 v[48:49], v[50:51], 0, v[48:49]
	v_bfe_u32 v45, v44, 7, 9
	v_mov_b32_e32 v37, v35
	v_lshl_add_u64 v[46:47], v[46:47], 0, v[34:35]
	v_cmp_lt_u32_e32 vcc, 31, v45
	v_lshl_add_u64 v[48:49], v[48:49], 0, v[36:37]
	s_waitcnt vmcnt(0)
	v_mov_b32_e32 v50, v26
	v_mov_b32_e32 v51, v22
	v_mov_b32_e32 v52, v30
	v_mov_b32_e32 v53, v18
	v_mov_b32_e32 v54, v10
	v_mov_b32_e32 v55, v6
	v_mov_b32_e32 v56, v14
	v_mov_b32_e32 v57, v2
	v_bfe_u32 v58, v26, 16, 1
	v_bfe_u32 v60, v28, 16, 1
	v_pk_add_f32 v[50:51], v[50:51], v[52:53]
	v_bfe_u32 v59, v27, 16, 1
	v_bfe_u32 v61, v29, 16, 1
	v_bfe_u32 v62, v30, 16, 1
	v_bfe_u32 v64, v32, 16, 1
	v_pk_add_f32 v[52:53], v[54:55], v[56:57]
	v_add3_u32 v54, v26, v58, s36
	v_add3_u32 v56, v28, v60, s36
	v_add_f32_e32 v50, 0, v50
	v_bfe_u32 v63, v31, 16, 1
	v_bfe_u32 v65, v33, 16, 1
	v_add3_u32 v55, v27, v59, s36
	v_add3_u32 v57, v29, v61, s36
	v_add3_u32 v58, v30, v62, s36
	v_add3_u32 v60, v32, v64, s36
	v_lshrrev_b32_e32 v54, 16, v54
	v_lshrrev_b32_e32 v56, 16, v56
	v_add_f32_e32 v62, v50, v51
	v_add3_u32 v59, v31, v63, s36
	v_add3_u32 v61, v33, v65, s36
	v_lshrrev_b32_e32 v58, 16, v58
	v_lshrrev_b32_e32 v60, 16, v60
	v_and_or_b32 v50, v55, s37, v54
	v_and_or_b32 v51, v57, s37, v56
	v_add_f32_e32 v52, v62, v52
	v_and_or_b32 v54, v59, s37, v58
	v_and_or_b32 v55, v61, s37, v60
	v_add_f32_e32 v52, v52, v53
	global_store_dwordx2 v[46:47], v[50:51], off sc1 nt
	global_store_dwordx2 v[48:49], v[54:55], off sc1 nt
	s_and_saveexec_b64 s[26:27], vcc
	s_cbranch_execz .LBB0_434
	v_lshl_or_b32 v40, v40, 9, v45
	v_subrev_u32_e32 v40, 32, v40
	v_and_b32_e32 v46, 0x1fc, v41
	v_ashrrev_i32_e32 v41, 31, v40
	v_lshlrev_b64 v[40:41], 11, v[40:41]
	v_lshl_or_b32 v40, v46, 2, v40
	v_lshl_add_u64 v[46:47], s[24:25], 0, v[40:41]
	global_store_dwordx4 v[46:47], v[26:29], off sc0 sc1 nt
	s_nop 1
	v_lshl_add_u64 v[26:27], s[16:17], 0, v[40:41]
	global_store_dwordx4 v[26:27], v[30:33], off sc0 sc1 nt
	s_nop 1
.LBB0_434:
	s_or_b64 exec, exec, s[26:27]
	v_add_u32_e32 v29, 64, v44
	v_lshlrev_b32_e32 v27, 2, v29
	v_ashrrev_i32_e32 v26, 16, v29
	v_lshrrev_b32_e32 v30, 7, v29
	v_bfe_u32 v31, v27, 6, 3
	v_lshl_or_b32 v31, v26, 3, v31
	v_bfe_u32 v30, v30, 5, 4
	v_mad_i32_i24 v30, v31, 17, v30
	v_ashrrev_i32_e32 v31, 31, v30
	v_bfe_u32 v28, v29, 7, 9
	v_lshlrev_b64 v[30:31], 12, v[30:31]
	v_bfe_u32 v29, v29, 7, 5
	v_lshl_add_u64 v[32:33], v[42:43], 0, v[30:31]
	v_lshlrev_b32_e32 v40, 4, v29
	v_mov_b32_e32 v41, v35
	v_lshl_add_u64 v[32:33], v[32:33], 0, v[40:41]
	v_bfe_u32 v40, v22, 16, 1
	v_add3_u32 v40, v22, v40, s36
	v_bfe_u32 v41, v23, 16, 1
	v_lshrrev_b32_e32 v40, 16, v40
	v_add3_u32 v41, v23, v41, s36
	v_and_or_b32 v40, v41, s37, v40
	v_bfe_u32 v41, v24, 16, 1
	v_add3_u32 v41, v24, v41, s36
	v_bfe_u32 v45, v25, 16, 1
	v_lshrrev_b32_e32 v41, 16, v41
	v_add3_u32 v45, v25, v45, s36
	v_lshl_add_u64 v[32:33], v[32:33], 0, v[34:35]
	v_and_or_b32 v41, v45, s37, v41
	global_store_dwordx2 v[32:33], v[40:41], off sc1 nt
	v_lshl_add_u64 v[30:31], v[38:39], 0, v[30:31]
	v_lshlrev_b32_e32 v32, 6, v29
	v_mov_b32_e32 v33, v35
	v_bfe_u32 v29, v18, 16, 1
	v_lshl_add_u64 v[30:31], v[30:31], 0, v[32:33]
	v_add3_u32 v29, v18, v29, s36
	v_bfe_u32 v32, v19, 16, 1
	v_lshrrev_b32_e32 v29, 16, v29
	v_add3_u32 v32, v19, v32, s36
	v_and_or_b32 v32, v32, s37, v29
	v_bfe_u32 v29, v20, 16, 1
	v_add3_u32 v29, v20, v29, s36
	v_bfe_u32 v33, v21, 16, 1
	v_lshrrev_b32_e32 v29, 16, v29
	v_add3_u32 v33, v21, v33, s36
	v_lshl_add_u64 v[30:31], v[30:31], 0, v[36:37]
	v_and_or_b32 v33, v33, s37, v29
	v_cmp_lt_u32_e32 vcc, 31, v28
	global_store_dwordx2 v[30:31], v[32:33], off sc1 nt
	s_and_saveexec_b64 s[26:27], vcc
	s_cbranch_execz .LBB0_436
	v_lshl_or_b32 v26, v26, 9, v28
	v_subrev_u32_e32 v26, 32, v26
	v_and_b32_e32 v29, 0x1fc, v27
	v_ashrrev_i32_e32 v27, 31, v26
	v_lshlrev_b64 v[26:27], 11, v[26:27]
	v_lshl_or_b32 v26, v29, 2, v26
	v_lshl_add_u64 v[28:29], s[24:25], 0, v[26:27]
	global_store_dwordx4 v[28:29], v[22:25], off sc0 sc1 nt
	s_nop 1
	v_lshl_add_u64 v[22:23], s[16:17], 0, v[26:27]
	global_store_dwordx4 v[22:23], v[18:21], off sc0 sc1 nt
	s_nop 1
.LBB0_436:
	s_or_b64 exec, exec, s[26:27]
	v_add_u32_e32 v21, 0x80, v44
	v_lshlrev_b32_e32 v19, 2, v21
	v_ashrrev_i32_e32 v18, 16, v21
	v_lshrrev_b32_e32 v22, 7, v21
	v_bfe_u32 v23, v19, 6, 3
	v_lshl_or_b32 v23, v18, 3, v23
	v_bfe_u32 v22, v22, 5, 4
	v_mad_i32_i24 v22, v23, 17, v22
	v_ashrrev_i32_e32 v23, 31, v22
	v_bfe_u32 v20, v21, 7, 9
	v_lshlrev_b64 v[22:23], 12, v[22:23]
	v_bfe_u32 v21, v21, 7, 5
	v_lshl_add_u64 v[24:25], v[42:43], 0, v[22:23]
	v_lshlrev_b32_e32 v26, 4, v21
	v_mov_b32_e32 v27, v35
	v_lshl_add_u64 v[24:25], v[24:25], 0, v[26:27]
	v_bfe_u32 v26, v10, 16, 1
	v_add3_u32 v26, v10, v26, s36
	v_bfe_u32 v27, v11, 16, 1
	v_lshrrev_b32_e32 v26, 16, v26
	v_add3_u32 v27, v11, v27, s36
	v_and_or_b32 v26, v27, s37, v26
	v_bfe_u32 v27, v12, 16, 1
	v_add3_u32 v27, v12, v27, s36
	v_bfe_u32 v28, v13, 16, 1
	v_lshrrev_b32_e32 v27, 16, v27
	v_add3_u32 v28, v13, v28, s36
	v_lshl_add_u64 v[24:25], v[24:25], 0, v[34:35]
	v_and_or_b32 v27, v28, s37, v27
	global_store_dwordx2 v[24:25], v[26:27], off sc1 nt
	v_lshl_add_u64 v[22:23], v[38:39], 0, v[22:23]
	v_lshlrev_b32_e32 v24, 6, v21
	v_mov_b32_e32 v25, v35
	v_bfe_u32 v21, v14, 16, 1
	v_lshl_add_u64 v[22:23], v[22:23], 0, v[24:25]
	v_add3_u32 v21, v14, v21, s36
	v_bfe_u32 v24, v15, 16, 1
	v_lshrrev_b32_e32 v21, 16, v21
	v_add3_u32 v24, v15, v24, s36
	v_and_or_b32 v24, v24, s37, v21
	v_bfe_u32 v21, v16, 16, 1
	v_add3_u32 v21, v16, v21, s36
	v_bfe_u32 v25, v17, 16, 1
	v_lshrrev_b32_e32 v21, 16, v21
	v_add3_u32 v25, v17, v25, s36
	v_lshl_add_u64 v[22:23], v[22:23], 0, v[36:37]
	v_and_or_b32 v25, v25, s37, v21
	v_cmp_lt_u32_e32 vcc, 31, v20
	global_store_dwordx2 v[22:23], v[24:25], off sc1 nt
	s_and_saveexec_b64 s[26:27], vcc
	s_cbranch_execz .LBB0_438
	v_lshl_or_b32 v18, v18, 9, v20
	v_subrev_u32_e32 v18, 32, v18
	v_and_b32_e32 v21, 0x1fc, v19
	v_ashrrev_i32_e32 v19, 31, v18
	v_lshlrev_b64 v[18:19], 11, v[18:19]
	v_lshl_or_b32 v18, v21, 2, v18
	v_lshl_add_u64 v[20:21], s[24:25], 0, v[18:19]
	global_store_dwordx4 v[20:21], v[10:13], off sc0 sc1 nt
	s_nop 1
	v_lshl_add_u64 v[10:11], s[16:17], 0, v[18:19]
	global_store_dwordx4 v[10:11], v[14:17], off sc0 sc1 nt
	s_nop 1
.LBB0_438:
	s_or_b64 exec, exec, s[26:27]
	v_add_u32_e32 v13, 0xc0, v44
	v_lshlrev_b32_e32 v11, 2, v13
	v_ashrrev_i32_e32 v10, 16, v13
	v_lshrrev_b32_e32 v14, 7, v13
	v_bfe_u32 v15, v11, 6, 3
	v_lshl_or_b32 v15, v10, 3, v15
	v_bfe_u32 v14, v14, 5, 4
	v_mad_i32_i24 v14, v15, 17, v14
	v_ashrrev_i32_e32 v15, 31, v14
	v_bfe_u32 v12, v13, 7, 9
	v_lshlrev_b64 v[14:15], 12, v[14:15]
	v_bfe_u32 v13, v13, 7, 5
	v_lshl_add_u64 v[16:17], v[42:43], 0, v[14:15]
	v_lshlrev_b32_e32 v18, 4, v13
	v_mov_b32_e32 v19, v35
	v_lshl_add_u64 v[16:17], v[16:17], 0, v[18:19]
	v_bfe_u32 v18, v6, 16, 1
	v_add3_u32 v18, v6, v18, s36
	v_bfe_u32 v19, v7, 16, 1
	v_lshrrev_b32_e32 v18, 16, v18
	v_add3_u32 v19, v7, v19, s36
	v_and_or_b32 v18, v19, s37, v18
	v_bfe_u32 v19, v8, 16, 1
	v_add3_u32 v19, v8, v19, s36
	v_bfe_u32 v20, v9, 16, 1
	v_lshrrev_b32_e32 v19, 16, v19
	v_add3_u32 v20, v9, v20, s36
	v_lshl_add_u64 v[16:17], v[16:17], 0, v[34:35]
	v_and_or_b32 v19, v20, s37, v19
	v_lshlrev_b32_e32 v34, 6, v13
	v_bfe_u32 v13, v2, 16, 1
	global_store_dwordx2 v[16:17], v[18:19], off sc1 nt
	v_add3_u32 v13, v2, v13, s36
	v_bfe_u32 v16, v3, 16, 1
	v_lshrrev_b32_e32 v13, 16, v13
	v_add3_u32 v16, v3, v16, s36
	v_and_or_b32 v16, v16, s37, v13
	v_bfe_u32 v13, v4, 16, 1
	v_lshl_add_u64 v[14:15], v[38:39], 0, v[14:15]
	v_add3_u32 v13, v4, v13, s36
	v_bfe_u32 v17, v5, 16, 1
	v_lshl_add_u64 v[14:15], v[14:15], 0, v[34:35]
	v_lshrrev_b32_e32 v13, 16, v13
	v_add3_u32 v17, v5, v17, s36
	v_lshl_add_u64 v[14:15], v[14:15], 0, v[36:37]
	v_and_or_b32 v17, v17, s37, v13
	v_cmp_lt_u32_e32 vcc, 31, v12
	global_store_dwordx2 v[14:15], v[16:17], off sc1 nt
	s_and_saveexec_b64 s[26:27], vcc
	s_cbranch_execz .LBB0_415
	v_lshl_or_b32 v10, v10, 9, v12
	v_subrev_u32_e32 v10, 32, v10
	v_and_b32_e32 v13, 0x1fc, v11
	v_ashrrev_i32_e32 v11, 31, v10
	v_lshlrev_b64 v[10:11], 11, v[10:11]
	v_lshl_or_b32 v10, v13, 2, v10
	v_lshl_add_u64 v[12:13], s[24:25], 0, v[10:11]
	global_store_dwordx4 v[12:13], v[6:9], off sc0 sc1 nt
	s_nop 1
	v_lshl_add_u64 v[6:7], s[16:17], 0, v[10:11]
	global_store_dwordx4 v[6:7], v[2:5], off sc0 sc1 nt
	s_nop 1
	s_branch .LBB0_415
